# FoX tile bodies: first two PV MFMA pairs issued inside the softmax tail (after 20 and 32 exps) instead of behind it
# speedup vs baseline: 1.0020x; 1.0011x over previous
.LBB0_843:
	v_exp_f32_e32 v96, v64
	v_exp_f32_e32 v64, v80
	v_exp_f32_e32 v97, v65
	v_exp_f32_e32 v65, v81
	v_exp_f32_e32 v98, v66
	v_exp_f32_e32 v66, v82
	v_exp_f32_e32 v99, v67
	v_exp_f32_e32 v67, v83
	v_exp_f32_e32 v100, v68
	v_exp_f32_e32 v68, v84
	v_exp_f32_e32 v101, v69
	v_exp_f32_e32 v69, v85
	v_exp_f32_e32 v102, v70
	v_exp_f32_e32 v70, v86
	v_exp_f32_e32 v103, v71
	v_exp_f32_e32 v71, v87
	v_cvt_pk_bf16_f32 v80, v96, v97
	v_cvt_pk_bf16_f32 v81, v98, v99
	v_cvt_pk_bf16_f32 v82, v100, v101
	v_cvt_pk_bf16_f32 v83, v102, v103
	v_exp_f32_e32 v104, v72
	v_exp_f32_e32 v72, v88
	v_exp_f32_e32 v105, v73
	v_exp_f32_e32 v73, v89
	s_setprio 1
	v_mfma_f32_32x32x16_bf16 v[32:47], v[4:7], v[80:83], v[32:47]
	s_waitcnt lgkmcnt(12)
	v_mfma_f32_32x32x16_bf16 v[16:31], v[8:11], v[80:83], v[16:31]
	s_setprio 0
	v_exp_f32_e32 v106, v74
	v_exp_f32_e32 v74, v90
	v_exp_f32_e32 v107, v75
	v_exp_f32_e32 v75, v91
	v_exp_f32_e32 v108, v76
	v_exp_f32_e32 v76, v92
	v_exp_f32_e32 v109, v77
	v_exp_f32_e32 v77, v93
	v_exp_f32_e32 v110, v78
	v_exp_f32_e32 v78, v94
	v_exp_f32_e32 v111, v79
	v_exp_f32_e32 v79, v95
	v_cvt_pk_bf16_f32 v84, v104, v105
	v_cvt_pk_bf16_f32 v85, v106, v107
	v_cvt_pk_bf16_f32 v86, v108, v109
	v_cvt_pk_bf16_f32 v87, v110, v111
	v_add_f32_e32 v0, v96, v64
	v_add_f32_e32 v1, v97, v65
	s_setprio 1
	s_waitcnt lgkmcnt(10)
	v_mfma_f32_32x32x16_bf16 v[32:47], v[12:15], v[84:87], v[32:47]
	s_waitcnt lgkmcnt(8)
	v_mfma_f32_32x32x16_bf16 v[16:31], v[148:151], v[84:87], v[16:31]
	s_setprio 0
	v_add_f32_e32 v3, v98, v66
	v_add_f32_e32 v212, v99, v67
	v_add_f32_e32 v0, v0, v100
	v_add_f32_e32 v1, v1, v101
	v_add_f32_e32 v3, v3, v102
	v_add_f32_e32 v212, v212, v103
	v_add_f32_e32 v0, v0, v68
	v_add_f32_e32 v1, v1, v69
	v_add_f32_e32 v3, v3, v70
	v_add_f32_e32 v212, v212, v71
	v_add_f32_e32 v0, v0, v104
	v_add_f32_e32 v1, v1, v105
	v_add_f32_e32 v3, v3, v106
	v_add_f32_e32 v212, v212, v107
	v_add_f32_e32 v0, v0, v72
	v_add_f32_e32 v1, v1, v73
	v_add_f32_e32 v3, v3, v74
	v_add_f32_e32 v212, v212, v75
	v_add_f32_e32 v0, v0, v108
	v_add_f32_e32 v1, v1, v109
	v_add_f32_e32 v3, v3, v110
	v_add_f32_e32 v212, v212, v111
	v_add_f32_e32 v0, v0, v76
	v_add_f32_e32 v1, v1, v77
	v_add_f32_e32 v3, v3, v78
	v_add_f32_e32 v212, v212, v79
	v_add_f32_e32 v0, v0, v1
	v_add_f32_e32 v1, v3, v212
	v_add_f32_e32 v0, v0, v1
	v_add_f32_e32 v180, v180, v0
	v_cvt_pk_bf16_f32 v64, v64, v65
	v_cvt_pk_bf16_f32 v65, v66, v67
	v_cvt_pk_bf16_f32 v66, v68, v69
	v_cvt_pk_bf16_f32 v67, v70, v71
	v_cvt_pk_bf16_f32 v68, v72, v73
	v_cvt_pk_bf16_f32 v69, v74, v75
	v_cvt_pk_bf16_f32 v70, v76, v77
	v_cvt_pk_bf16_f32 v71, v78, v79
	s_setprio 1
	s_waitcnt lgkmcnt(6)
	v_mfma_f32_32x32x16_bf16 v[32:47], v[152:155], v[64:67], v[32:47]
	s_waitcnt lgkmcnt(4)
	v_mfma_f32_32x32x16_bf16 v[16:31], v[156:159], v[64:67], v[16:31]
	s_waitcnt lgkmcnt(2)
	v_mfma_f32_32x32x16_bf16 v[32:47], v[160:163], v[68:71], v[32:47]
	s_waitcnt lgkmcnt(0)
	v_mfma_f32_32x32x16_bf16 v[16:31], v[164:167], v[68:71], v[16:31]
	s_setprio 0
	s_andn2_b64 vcc, exec, s[56:57]
	s_mov_b64 s[12:13], -1
	s_cbranch_vccz .LBB0_858

.LBB0_856:
	v_exp_f32_e32 v96, v64
	v_exp_f32_e32 v64, v80
	v_exp_f32_e32 v97, v65
	v_exp_f32_e32 v65, v81
	v_exp_f32_e32 v98, v66
	v_exp_f32_e32 v66, v82
	v_exp_f32_e32 v99, v67
	v_exp_f32_e32 v67, v83
	v_exp_f32_e32 v100, v68
	v_exp_f32_e32 v68, v84
	v_exp_f32_e32 v101, v69
	v_exp_f32_e32 v69, v85
	v_exp_f32_e32 v102, v70
	v_exp_f32_e32 v70, v86
	v_exp_f32_e32 v103, v71
	v_exp_f32_e32 v71, v87
	v_cvt_pk_bf16_f32 v80, v96, v97
	v_cvt_pk_bf16_f32 v81, v98, v99
	v_cvt_pk_bf16_f32 v82, v100, v101
	v_cvt_pk_bf16_f32 v83, v102, v103
	v_exp_f32_e32 v104, v72
	v_exp_f32_e32 v72, v88
	v_exp_f32_e32 v105, v73
	v_exp_f32_e32 v73, v89
	s_setprio 1
	v_mfma_f32_32x32x16_bf16 v[32:47], v[4:7], v[80:83], v[32:47]
	s_waitcnt lgkmcnt(12)
	v_mfma_f32_32x32x16_bf16 v[16:31], v[8:11], v[80:83], v[16:31]
	s_setprio 0
	v_exp_f32_e32 v106, v74
	v_exp_f32_e32 v74, v90
	v_exp_f32_e32 v107, v75
	v_exp_f32_e32 v75, v91
	v_exp_f32_e32 v108, v76
	v_exp_f32_e32 v76, v92
	v_exp_f32_e32 v109, v77
	v_exp_f32_e32 v77, v93
	v_exp_f32_e32 v110, v78
	v_exp_f32_e32 v78, v94
	v_exp_f32_e32 v111, v79
	v_exp_f32_e32 v79, v95
	v_cvt_pk_bf16_f32 v84, v104, v105
	v_cvt_pk_bf16_f32 v85, v106, v107
	v_cvt_pk_bf16_f32 v86, v108, v109
	v_cvt_pk_bf16_f32 v87, v110, v111
	v_add_f32_e32 v0, v96, v64
	v_add_f32_e32 v1, v97, v65
	s_setprio 1
	s_waitcnt lgkmcnt(10)
	v_mfma_f32_32x32x16_bf16 v[32:47], v[12:15], v[84:87], v[32:47]
	s_waitcnt lgkmcnt(8)
	v_mfma_f32_32x32x16_bf16 v[16:31], v[148:151], v[84:87], v[16:31]
	s_setprio 0
	v_add_f32_e32 v3, v98, v66
	v_add_f32_e32 v212, v99, v67
	v_add_f32_e32 v0, v0, v100
	v_add_f32_e32 v1, v1, v101
	v_add_f32_e32 v3, v3, v102
	v_add_f32_e32 v212, v212, v103
	v_add_f32_e32 v0, v0, v68
	v_add_f32_e32 v1, v1, v69
	v_add_f32_e32 v3, v3, v70
	v_add_f32_e32 v212, v212, v71
	v_add_f32_e32 v0, v0, v104
	v_add_f32_e32 v1, v1, v105
	v_add_f32_e32 v3, v3, v106
	v_add_f32_e32 v212, v212, v107
	v_add_f32_e32 v0, v0, v72
	v_add_f32_e32 v1, v1, v73
	v_add_f32_e32 v3, v3, v74
	v_add_f32_e32 v212, v212, v75
	v_add_f32_e32 v0, v0, v108
	v_add_f32_e32 v1, v1, v109
	v_add_f32_e32 v3, v3, v110
	v_add_f32_e32 v212, v212, v111
	v_add_f32_e32 v0, v0, v76
	v_add_f32_e32 v1, v1, v77
	v_add_f32_e32 v3, v3, v78
	v_add_f32_e32 v212, v212, v79
	v_add_f32_e32 v0, v0, v1
	v_add_f32_e32 v1, v3, v212
	v_add_f32_e32 v0, v0, v1
	v_add_f32_e32 v180, v180, v0
	v_cvt_pk_bf16_f32 v64, v64, v65
	v_cvt_pk_bf16_f32 v65, v66, v67
	v_cvt_pk_bf16_f32 v66, v68, v69
	v_cvt_pk_bf16_f32 v67, v70, v71
	v_cvt_pk_bf16_f32 v68, v72, v73
	v_cvt_pk_bf16_f32 v69, v74, v75
	v_cvt_pk_bf16_f32 v70, v76, v77
	v_cvt_pk_bf16_f32 v71, v78, v79
	s_setprio 1
	s_waitcnt lgkmcnt(6)
	v_mfma_f32_32x32x16_bf16 v[32:47], v[152:155], v[64:67], v[32:47]
	s_waitcnt lgkmcnt(4)
	v_mfma_f32_32x32x16_bf16 v[16:31], v[156:159], v[64:67], v[16:31]
	s_waitcnt lgkmcnt(2)
	v_mfma_f32_32x32x16_bf16 v[32:47], v[160:163], v[68:71], v[32:47]
	s_waitcnt lgkmcnt(0)
	v_mfma_f32_32x32x16_bf16 v[16:31], v[164:167], v[68:71], v[16:31]
	s_setprio 0
	s_add_i32 s2, s63, 0xffffff81
	s_cmp_gt_i32 s2, s61
	s_cbranch_scc0 .LBB0_833
